# v114 + the two IEEE division chains in the RWKV helper's group-norm stage replaced by v_rcp (same treatment as the other 358 chains)
# speedup vs baseline: 1.0010x; 1.0010x over previous
.LBB0_601:
	s_cmp_lt_i32 s2, 1
	s_cbranch_scc1 .LBB0_603
	s_add_i32 s3, s2, -1
	ds_read_b128 v[8:11], v132 offset:28672
	s_mul_hi_u32 s0, s3, 0xaaaaaaab
	s_lshr_b32 s0, s0, 1
	s_mul_i32 s0, s0, 3
	s_sub_i32 s0, s3, s0
	v_lshl_add_u32 v12, s0, 6, v89
	ds_read_b32 v56, v12
	s_waitcnt lgkmcnt(1)
	v_mov_b32_e32 v12, v9
	v_mov_b32_e32 v13, v10
	v_mov_b32_e32 v14, v8
	v_mov_b32_e32 v15, v11
	v_pk_add_f32 v[12:13], v[12:13], v[14:15]
	s_mov_b32 s0, 0xf800000
	v_add_f32_e32 v12, v12, v13
	v_readlane_b32 s18, v254, 22
	v_readlane_b32 s19, v254, 23
	v_add_f32_dpp v12, v12, v12 quad_perm:[1,0,3,2] row_mask:0xf bank_mask:0xf bound_ctrl:1
	s_nop 1
	v_add_f32_dpp v12, v12, v12 quad_perm:[2,3,0,1] row_mask:0xf bank_mask:0xf bound_ctrl:1
	s_nop 1
	v_add_f32_dpp v12, v12, v12 row_half_mirror row_mask:0xf bank_mask:0xf bound_ctrl:1
	s_nop 1
	v_add_f32_dpp v12, v12, v12 row_mirror row_mask:0xf bank_mask:0xf bound_ctrl:1
	v_fmamk_f32 v9, v12, 0xbc800000, v9
	v_fmamk_f32 v8, v12, 0xbc800000, v8
	v_fmamk_f32 v11, v12, 0xbc800000, v11
	v_fmac_f32_e32 v10, 0xbc800000, v12
	v_pk_mul_f32 v[12:13], v[10:11], v[10:11]
	v_pk_mul_f32 v[14:15], v[8:9], v[8:9]
	s_nop 0
	v_pk_mov_b32 v[52:53], v[14:15], v[12:13] op_sel:[1,0]
	v_mov_b32_e32 v15, v13
	v_pk_add_f32 v[12:13], v[52:53], v[14:15]
	s_nop 0
	v_add_f32_e32 v12, v12, v13
	s_nop 1
	v_add_f32_dpp v12, v12, v12 quad_perm:[1,0,3,2] row_mask:0xf bank_mask:0xf bound_ctrl:1
	s_nop 1
	v_add_f32_dpp v12, v12, v12 quad_perm:[2,3,0,1] row_mask:0xf bank_mask:0xf bound_ctrl:1
	s_nop 1
	v_add_f32_dpp v12, v12, v12 row_half_mirror row_mask:0xf bank_mask:0xf bound_ctrl:1
	s_nop 1
	v_add_f32_dpp v12, v12, v12 row_mirror row_mask:0xf bank_mask:0xf bound_ctrl:1
	v_fmamk_f32 v12, v12, 0x3c800000, v190
	v_mul_f32_e32 v13, 0x4f800000, v12
	v_cmp_gt_f32_e32 vcc, s0, v12
	s_nop 1
	v_cndmask_b32_e32 v12, v12, v13, vcc
	v_sqrt_f32_e32 v13, v12
	s_nop 0
	v_add_u32_e32 v14, -1, v13
	v_fma_f32 v15, -v14, v13, v12
	v_cmp_ge_f32_e64 s[0:1], 0, v15
	v_add_u32_e32 v15, 1, v13
	s_nop 0
	v_cndmask_b32_e64 v14, v13, v14, s[0:1]
	v_fma_f32 v13, -v15, v13, v12
	v_cmp_lt_f32_e64 s[0:1], 0, v13
	s_nop 1
	v_cndmask_b32_e64 v13, v14, v15, s[0:1]
	v_mul_f32_e32 v14, 0x37800000, v13
	v_cndmask_b32_e32 v13, v13, v14, vcc
	v_cmp_class_f32_e32 vcc, v12, v189
	s_nop 1
	v_cndmask_b32_e32 v57, v13, v12, vcc
	ds_read_b128 v[12:15], v132 offset:24576
	ds_read_b128 v[52:55], v132 offset:20480
	s_lshl_b32 s0, s3, 4
	s_mov_b32 s1, s18
	v_rcp_f32_e32 v58, v57
	s_nop 0
	v_pk_mul_f32 v[8:9], v[8:9], v[58:59] op_sel_hi:[1,0]
	v_pk_mul_f32 v[10:11], v[10:11], v[58:59] op_sel_hi:[1,0]
	s_waitcnt vmcnt(0)
	v_pk_fma_f32 v[8:9], v[16:17], v[8:9], v[20:21]
	v_pk_fma_f32 v[10:11], v[18:19], v[10:11], v[22:23]
	s_waitcnt lgkmcnt(0)
	v_pk_fma_f32 v[8:9], v[52:53], v[56:57], v[8:9] op_sel_hi:[1,0,1]
	v_pk_fma_f32 v[10:11], v[54:55], v[56:57], v[10:11] op_sel_hi:[1,0,1]
	v_pk_mul_f32 v[8:9], v[12:13], v[8:9]
	v_pk_mul_f32 v[10:11], v[14:15], v[10:11]
	v_cvt_pk_bf16_f32 v8, v8, v9
	s_movk_i32 s3, 0x3080
	v_cvt_pk_bf16_f32 v9, v10, v11
	v_lshl_add_u64 v[10:11], v[28:29], 0, s[0:1]
	v_mad_u64_u32 v[12:13], s[0:1], v10, s3, v[110:111]
	v_mov_b32_e32 v10, v13
	v_mad_u64_u32 v[10:11], s[0:1], v11, s3, v[10:11]
	v_mov_b32_e32 v13, v10
	global_store_dwordx2 v[12:13], v[8:9], off offset:2048

.LBB0_617:
	s_add_i32 s3, s2, 2
	s_and_b64 vcc, exec, s[0:1]
	s_cbranch_vccz .LBB0_588
	ds_read_b128 v[8:11], v133
	ds_read_b128 v[12:15], v134
	s_cmp_lt_i32 s2, 0
	s_waitcnt lgkmcnt(0)
	v_mfma_f32_16x16x32_bf16 v[8:11], v[8:11], v[12:15], 0
	ds_read_b128 v[12:15], v133 offset:64
	ds_read_b128 v[52:55], v134 offset:64
	s_waitcnt lgkmcnt(0)
	v_mfma_f32_16x16x32_bf16 v[8:11], v[12:15], v[52:55], v[8:11]
	ds_read_b128 v[12:15], v133 offset:128
	ds_read_b128 v[52:55], v134 offset:128
	s_waitcnt lgkmcnt(0)
	v_mfma_f32_16x16x32_bf16 v[8:11], v[12:15], v[52:55], v[8:11]
	ds_read_b128 v[12:15], v133 offset:192
	ds_read_b128 v[52:55], v134 offset:192
	s_waitcnt lgkmcnt(0)
	v_mfma_f32_16x16x32_bf16 v[8:11], v[12:15], v[52:55], v[8:11]
	s_nop 7
	ds_write2st64_b32 v138, v8, v9 offset0:96 offset1:97
	ds_write2st64_b32 v138, v10, v11 offset0:98 offset1:99
	s_cbranch_scc1 .LBB0_620
	ds_read_b128 v[8:11], v132 offset:61952
	s_mul_hi_u32 s0, s2, 0xaaaaaaab
	s_lshr_b32 s0, s0, 1
	s_mul_i32 s0, s0, 3
	s_sub_i32 s0, s2, s0
	v_lshl_add_u32 v12, s0, 6, v89
	ds_read_b32 v56, v12
	s_waitcnt lgkmcnt(1)
	v_mov_b32_e32 v12, v9
	v_mov_b32_e32 v13, v10
	v_mov_b32_e32 v14, v8
	v_mov_b32_e32 v15, v11
	v_pk_add_f32 v[12:13], v[12:13], v[14:15]
	s_mov_b32 s0, 0xf800000
	v_add_f32_e32 v12, v12, v13
	v_readlane_b32 s18, v254, 22
	s_movk_i32 s5, 0x3080
	v_add_f32_dpp v12, v12, v12 quad_perm:[1,0,3,2] row_mask:0xf bank_mask:0xf bound_ctrl:1
	v_readlane_b32 s19, v254, 23
	s_nop 0
	v_add_f32_dpp v12, v12, v12 quad_perm:[2,3,0,1] row_mask:0xf bank_mask:0xf bound_ctrl:1
	s_nop 1
	v_add_f32_dpp v12, v12, v12 row_half_mirror row_mask:0xf bank_mask:0xf bound_ctrl:1
	s_nop 1
	v_add_f32_dpp v12, v12, v12 row_mirror row_mask:0xf bank_mask:0xf bound_ctrl:1
	v_fmamk_f32 v9, v12, 0xbc800000, v9
	v_fmamk_f32 v8, v12, 0xbc800000, v8
	v_fmamk_f32 v11, v12, 0xbc800000, v11
	v_fmac_f32_e32 v10, 0xbc800000, v12
	v_pk_mul_f32 v[12:13], v[10:11], v[10:11]
	v_pk_mul_f32 v[14:15], v[8:9], v[8:9]
	s_nop 0
	v_pk_mov_b32 v[52:53], v[14:15], v[12:13] op_sel:[1,0]
	v_mov_b32_e32 v15, v13
	v_pk_add_f32 v[12:13], v[52:53], v[14:15]
	s_nop 0
	v_add_f32_e32 v12, v12, v13
	s_nop 1
	v_add_f32_dpp v12, v12, v12 quad_perm:[1,0,3,2] row_mask:0xf bank_mask:0xf bound_ctrl:1
	s_nop 1
	v_add_f32_dpp v12, v12, v12 quad_perm:[2,3,0,1] row_mask:0xf bank_mask:0xf bound_ctrl:1
	s_nop 1
	v_add_f32_dpp v12, v12, v12 row_half_mirror row_mask:0xf bank_mask:0xf bound_ctrl:1
	s_nop 1
	v_add_f32_dpp v12, v12, v12 row_mirror row_mask:0xf bank_mask:0xf bound_ctrl:1
	v_fmamk_f32 v12, v12, 0x3c800000, v190
	v_mul_f32_e32 v13, 0x4f800000, v12
	v_cmp_gt_f32_e32 vcc, s0, v12
	s_nop 1
	v_cndmask_b32_e32 v12, v12, v13, vcc
	v_sqrt_f32_e32 v13, v12
	s_nop 0
	v_add_u32_e32 v14, -1, v13
	v_fma_f32 v15, -v14, v13, v12
	v_cmp_ge_f32_e64 s[0:1], 0, v15
	v_add_u32_e32 v15, 1, v13
	s_nop 0
	v_cndmask_b32_e64 v14, v13, v14, s[0:1]
	v_fma_f32 v13, -v15, v13, v12
	v_cmp_lt_f32_e64 s[0:1], 0, v13
	s_nop 1
	v_cndmask_b32_e64 v13, v14, v15, s[0:1]
	v_mul_f32_e32 v14, 0x37800000, v13
	v_cndmask_b32_e32 v13, v13, v14, vcc
	v_cmp_class_f32_e32 vcc, v12, v189
	s_nop 1
	v_cndmask_b32_e32 v57, v13, v12, vcc
	ds_read_b128 v[12:15], v132 offset:57856
	ds_read_b128 v[52:55], v132 offset:53760
	s_lshl_b32 s0, s2, 4
	s_mov_b32 s1, s18
	v_rcp_f32_e32 v58, v57
	s_nop 0
	v_pk_mul_f32 v[8:9], v[8:9], v[58:59] op_sel_hi:[1,0]
	v_pk_mul_f32 v[10:11], v[10:11], v[58:59] op_sel_hi:[1,0]
	s_waitcnt vmcnt(0)
	v_pk_fma_f32 v[8:9], v[16:17], v[8:9], v[20:21]
	v_pk_fma_f32 v[10:11], v[18:19], v[10:11], v[22:23]
	s_waitcnt lgkmcnt(0)
	v_pk_fma_f32 v[8:9], v[52:53], v[56:57], v[8:9] op_sel_hi:[1,0,1]
	v_pk_fma_f32 v[10:11], v[54:55], v[56:57], v[10:11] op_sel_hi:[1,0,1]
	v_pk_mul_f32 v[8:9], v[12:13], v[8:9]
	v_pk_mul_f32 v[10:11], v[14:15], v[10:11]
	v_cvt_pk_bf16_f32 v8, v8, v9
	s_nop 0
	v_cvt_pk_bf16_f32 v9, v10, v11
	v_lshl_add_u64 v[10:11], v[28:29], 0, s[0:1]
	v_mad_u64_u32 v[12:13], s[0:1], v10, s5, v[110:111]
	v_mov_b32_e32 v10, v13
	v_mad_u64_u32 v[10:11], s[0:1], v11, s5, v[10:11]
	v_mov_b32_e32 v13, v10
	global_store_dwordx2 v[12:13], v[8:9], off offset:2048
